# lnpass-in-phase-6 version with the row-group split moved to 1480 (more rows on the scan workgroups)
# baseline (speedup 1.0000x reference)
;     __device__ __forceinline__ const float* in(int i) const { return (const float*)ptr(i); }
;     __device__ __forceinline__ unsigned char* ws() const { return (unsigned char*)ptr(37); }
; #define ws (p.ws())
; __device__ __forceinline__ void phase_lnpass(const Ctx& p) {
;     const int tid = threadIdx.x, c8 = tid & 7, h = (tid >> 3) & 7, rr = tid >> 6, c = h * 64 + 8 * c8;
;     const bf16_t* ZRW = (const bf16_t*)(p.ws() + WS_ZRW); const bf16_t* AB = (const bf16_t*)(p.ws() + WS_ABUF); const bf16_t* GG = (const bf16_t*)(p.ws() + WS_GG);
;     bf16_t* ORW = (bf16_t*)(p.ws() + WS_ORW);
;     float mur[8], muk[8], muv[8], kac[8], rkc[8], lg[8], lb[8];
; #pragma unroll
;     for (int e = 0; e < 8; ++e) { mur[e] = p.in(17)[c + e]; muk[e] = p.in(17)[512 + c + e]; muv[e] = p.in(17)[1024 + c + e]; kac[e] = p.in(24)[c + e]; rkc[e] = p.in(25)[c + e]; lg[e] = p.in(26)[c + e]; lb[e] = p.in(27)[c + e]; }
;     struct LR { u32x4 zr, zrp, zk, zkp, zv, zvp, ab, gg, yy; };
;     auto ldrow = [&](LR& L, int row) {
;         const int rp = row > 0 ? row - 1 : 0;
;         L.zr = *(const u32x4*)(ZRW + (size_t)row * SHW + c); L.zrp = *(const u32x4*)(ZRW + (size_t)rp * SHW + c);
;         L.zk = *(const u32x4*)(ZRW + (size_t)row * SHW + 512 + c); L.zkp = *(const u32x4*)(ZRW + (size_t)rp * SHW + 512 + c);
;         L.zv = *(const u32x4*)(ZRW + (size_t)row * SHW + 1024 + c); L.zvp = *(const u32x4*)(ZRW + (size_t)rp * SHW + 1024 + c);
;         L.ab = *(const u32x4*)(AB + (size_t)row * 512 + c); L.gg = *(const u32x4*)(GG + (size_t)row * 512 + c); L.yy = *(const u32x4*)(ORW + (size_t)row * 512 + c);
;     };
;     LR La, Lb;
;     if ((int)blockIdx.x < MR / 8) ldrow(La, blockIdx.x * 8 + rr);
;     for (int it = blockIdx.x; it < MR / 8; it += gridDim.x) {
;         const int row = it * 8 + rr;
;         const bool more = it + (int)gridDim.x < MR / 8;
;         if (more) ldrow(Lb, (it + gridDim.x) * 8 + rr);
.Lln_w1_x:
	s_or_b64 exec, exec, s[2:3]
	s_waitcnt lgkmcnt(0)
	s_barrier
	s_sub_u32 s70, s28, 4
	s_movk_i32 s72, 0x7c
	s_add_i32 s2, 0, 0x23528
	s_waitcnt vmcnt(0)
	v_mov_b32_e32 v0, s2
	ds_read_b64 v[0:1], v0
	s_add_i32 s2, 0, 0x23488
	v_mov_b32_e32 v2, s2
	s_add_i32 s6, 0, 0x234c0
	ds_read_b64 v[8:9], v2
	s_waitcnt lgkmcnt(0)
	v_readfirstlane_b32 s2, v0
	v_mov_b32_e32 v0, s6
	s_add_i32 s6, 0, 0x234d0
	v_mov_b32_e32 v4, s6
	v_readfirstlane_b32 s3, v1
	ds_read_b128 v[0:3], v0
	ds_read_b128 v[4:7], v4
	v_readfirstlane_b32 s12, v8
	v_readfirstlane_b32 s13, v9
	s_cmpk_gt_i32 s70, 0x5c7
	s_waitcnt lgkmcnt(1)
	v_readfirstlane_b32 s14, v0
	v_readfirstlane_b32 s15, v1
	v_readfirstlane_b32 s16, v2
	v_readfirstlane_b32 s17, v3
	s_waitcnt lgkmcnt(0)
	v_readfirstlane_b32 s10, v4
	v_readfirstlane_b32 s11, v5
	v_readfirstlane_b32 s8, v6
	v_readfirstlane_b32 s9, v7
	s_cbranch_scc1 .Lln1_done
	v_lshlrev_b32_e32 v0, 3, v180
	v_and_b32_e32 v56, 0x1f8, v0
	v_mov_b32_e32 v141, 0
	v_lshlrev_b32_e32 v140, 2, v56
	v_lshl_add_u64 v[32:33], s[12:13], 0, v[140:141]
	global_load_dwordx4 v[0:3], v140, s[12:13] offset:16
	global_load_dwordx4 v[4:7], v140, s[12:13]
	global_load_dwordx4 v[8:11], v140, s[12:13] offset:2064
	global_load_dwordx4 v[12:15], v140, s[12:13] offset:2048
	global_load_dwordx4 v[16:19], v140, s[14:15] offset:16
	global_load_dwordx4 v[20:23], v140, s[14:15]
	global_load_dwordx4 v[24:27], v140, s[16:17] offset:16
	global_load_dwordx4 v[28:31], v140, s[16:17]
	s_movk_i32 s12, 0x1000
	v_add_co_u32_e32 v60, vcc, s12, v32
	s_mov_b64 s[6:7], 0x1000
	s_nop 0
	v_addc_co_u32_e32 v61, vcc, 0, v33, vcc
	v_lshl_add_u64 v[58:59], v[32:33], 0, s[6:7]
	global_load_dwordx4 v[32:35], v[60:61], off
	global_load_dwordx4 v[36:39], v[58:59], off offset:16
	global_load_dwordx4 v[40:43], v140, s[10:11] offset:16
	global_load_dwordx4 v[44:47], v140, s[10:11]
	global_load_dwordx4 v[48:51], v140, s[8:9] offset:16
	global_load_dwordx4 v[52:55], v140, s[8:9]
	s_add_u32 s8, s2, 0x8340000
	s_addc_u32 s9, s3, 0
	s_add_u32 s10, s2, 0x4240000
	s_addc_u32 s11, s3, 0
	s_add_u32 s14, s2, 0x3200000
	v_lshrrev_b32_e32 v152, 6, v180
	s_addc_u32 s15, s3, 0
	s_lshl_b32 s12, s70, 3
	v_add_u32_e32 v58, s12, v152
	v_max_i32_e32 v57, 1, v58
	s_movk_i32 s13, 0xe00
	v_mov_b64_e32 v[60:61], s[8:9]
	v_add_u32_e32 v57, -1, v57
	v_mad_i64_i32 v[62:63], s[16:17], v58, s13, v[60:61]
	v_lshlrev_b32_e32 v140, 1, v56
	v_lshl_add_u64 v[62:63], v[62:63], 0, v[140:141]
	v_mad_u64_u32 v[60:61], s[16:17], v57, s13, v[60:61]
	v_ashrrev_i32_e32 v59, 31, v58
	v_lshl_add_u64 v[60:61], v[60:61], 0, v[140:141]
	global_load_dwordx4 v[104:107], v[62:63], off
	global_load_dwordx4 v[108:111], v[62:63], off offset:1024
	global_load_dwordx4 v[124:127], v[60:61], off
	global_load_dwordx4 v[92:95], v[62:63], off offset:2048
	global_load_dwordx4 v[116:119], v[60:61], off offset:1024
	global_load_dwordx4 v[120:123], v[60:61], off offset:2048
	v_lshlrev_b64 v[58:59], 10, v[58:59]
	v_lshl_add_u64 v[60:61], s[14:15], 0, v[58:59]
	v_lshl_add_u64 v[62:63], s[10:11], 0, v[58:59]
	v_lshl_add_u64 v[58:59], s[2:3], 0, v[58:59]
	v_lshl_add_u64 v[60:61], v[60:61], 0, v[140:141]
	v_lshl_add_u64 v[58:59], v[58:59], 0, v[140:141]
	v_lshl_add_u64 v[62:63], v[62:63], 0, v[140:141]
	global_load_dwordx4 v[112:115], v[60:61], off
	global_load_dwordx4 v[100:103], v[62:63], off
	global_load_dwordx4 v[96:99], v[58:59], off
	v_lshl_add_u64 v[146:147], s[2:3], 0, v[140:141]
	s_add_i32 s2, s70, s72
	v_lshl_add_u64 v[142:143], s[14:15], 0, v[140:141]
	v_lshl_add_u64 v[144:145], s[10:11], 0, v[140:141]
	v_lshl_add_u64 v[148:149], s[8:9], 0, v[140:141]
	s_lshl_b32 s14, s2, 3
	s_lshl_b32 s15, s72, 3
	s_movk_i32 s16, 0x4000
	s_movk_i32 s17, 0x3fff
	s_add_i32 s18, 0, 0x23428
	s_movk_i32 s19, 0x1c00
	v_lshlrev_b32_e32 v140, 2, v56
	v_mov_b32_e32 v153, 0x3a27c5ac
	s_mov_b32 s20, 0xf800000
	v_mov_b32_e32 v154, 0x260
	v_mov_b32_e32 v155, 0xfff
	s_mov_b32 s21, s70
	s_branch .Lln1_c

; __device__ __forceinline__ void phase_lnpass(const Ctx& p) {
;     ...
;     auto ldrow = [&](LR& L, int row) {
;         const int rp = row > 0 ? row - 1 : 0;
;         L.zr = *(const u32x4*)(ZRW + (size_t)row * SHW + c); L.zrp = *(const u32x4*)(ZRW + (size_t)rp * SHW + c);
;         L.zk = *(const u32x4*)(ZRW + (size_t)row * SHW + 512 + c); L.zkp = *(const u32x4*)(ZRW + (size_t)rp * SHW + 512 + c);
;         L.zv = *(const u32x4*)(ZRW + (size_t)row * SHW + 1024 + c); L.zvp = *(const u32x4*)(ZRW + (size_t)rp * SHW + 1024 + c);
;         L.ab = *(const u32x4*)(AB + (size_t)row * 512 + c); L.gg = *(const u32x4*)(GG + (size_t)row * 512 + c); L.yy = *(const u32x4*)(ORW + (size_t)row * 512 + c);
;     };
;     ...
;     for (int it = blockIdx.x; it < MR / 8; it += gridDim.x) {
;         const int row = it * 8 + rr;
;         const bool more = it + (int)gridDim.x < MR / 8;
;         if (more) ldrow(Lb, (it + gridDim.x) * 8 + rr);
.Lln1_c:
	s_add_i32 s21, s21, s72
	s_cmpk_gt_i32 s21, 0x5c7
	s_cselect_b64 s[8:9], -1, 0
	s_and_b64 vcc, exec, s[8:9]
	s_cbranch_vccnz .Lln1_d
	v_add_u32_e32 v80, s14, v152
	v_max_i32_e32 v56, 1, v80
	v_add_u32_e32 v56, -1, v56
	v_mad_i64_i32 v[68:69], s[2:3], v80, s13, v[148:149]
	v_mad_u64_u32 v[76:77], s[2:3], v56, s13, v[148:149]
	global_load_dwordx4 v[56:59], v[68:69], off
	global_load_dwordx4 v[64:67], v[68:69], off offset:1024
	global_load_dwordx4 v[60:63], v[76:77], off
	global_load_dwordx4 v[72:75], v[68:69], off offset:2048
	s_nop 0
	global_load_dwordx4 v[68:71], v[76:77], off offset:1024
	s_nop 0
	global_load_dwordx4 v[76:79], v[76:77], off offset:2048
	v_ashrrev_i32_e32 v81, 31, v80
	v_lshlrev_b64 v[88:89], 10, v[80:81]
	v_lshl_add_u64 v[80:81], v[142:143], 0, v[88:89]
	v_lshl_add_u64 v[84:85], v[144:145], 0, v[88:89]
	v_lshl_add_u64 v[88:89], v[146:147], 0, v[88:89]
	global_load_dwordx4 v[80:83], v[80:81], off
	s_nop 0
	global_load_dwordx4 v[84:87], v[84:85], off
	s_nop 0
	global_load_dwordx4 v[88:91], v[88:89], off

;     __device__ __forceinline__ const float* in(int i) const { return (const float*)ptr(i); }
;     __device__ __forceinline__ unsigned char* ws() const { return (unsigned char*)ptr(37); }
; #define ws (p.ws())
; __device__ __forceinline__ void phase_lnpass(const Ctx& p) {
;     const int tid = threadIdx.x, c8 = tid & 7, h = (tid >> 3) & 7, rr = tid >> 6, c = h * 64 + 8 * c8;
;     const bf16_t* ZRW = (const bf16_t*)(p.ws() + WS_ZRW); const bf16_t* AB = (const bf16_t*)(p.ws() + WS_ABUF); const bf16_t* GG = (const bf16_t*)(p.ws() + WS_GG);
;     bf16_t* ORW = (bf16_t*)(p.ws() + WS_ORW);
;     float mur[8], muk[8], muv[8], kac[8], rkc[8], lg[8], lb[8];
; #pragma unroll
;     for (int e = 0; e < 8; ++e) { mur[e] = p.in(17)[c + e]; muk[e] = p.in(17)[512 + c + e]; muv[e] = p.in(17)[1024 + c + e]; kac[e] = p.in(24)[c + e]; rkc[e] = p.in(25)[c + e]; lg[e] = p.in(26)[c + e]; lb[e] = p.in(27)[c + e]; }
;     struct LR { u32x4 zr, zrp, zk, zkp, zv, zvp, ab, gg, yy; };
;     auto ldrow = [&](LR& L, int row) {
;         const int rp = row > 0 ? row - 1 : 0;
;         L.zr = *(const u32x4*)(ZRW + (size_t)row * SHW + c); L.zrp = *(const u32x4*)(ZRW + (size_t)rp * SHW + c);
;         L.zk = *(const u32x4*)(ZRW + (size_t)row * SHW + 512 + c); L.zkp = *(const u32x4*)(ZRW + (size_t)rp * SHW + 512 + c);
;         L.zv = *(const u32x4*)(ZRW + (size_t)row * SHW + 1024 + c); L.zvp = *(const u32x4*)(ZRW + (size_t)rp * SHW + 1024 + c);
;         L.ab = *(const u32x4*)(AB + (size_t)row * 512 + c); L.gg = *(const u32x4*)(GG + (size_t)row * 512 + c); L.yy = *(const u32x4*)(ORW + (size_t)row * 512 + c);
;     };
;     LR La, Lb;
;     if ((int)blockIdx.x < MR / 8) ldrow(La, blockIdx.x * 8 + rr);
;     for (int it = blockIdx.x; it < MR / 8; it += gridDim.x) {
;         const int row = it * 8 + rr;
;         const bool more = it + (int)gridDim.x < MR / 8;
;         if (more) ldrow(Lb, (it + gridDim.x) * 8 + rr);
.Lln_w2_x:
	s_or_b64 exec, exec, s[2:3]
	s_waitcnt lgkmcnt(0)
	s_barrier
	s_movk_i32 s72, 0x80
	s_add_i32 s71, s28, 0x548
	s_add_i32 s2, 0, 0x23528
	s_waitcnt vmcnt(0)
	v_mov_b32_e32 v0, s2
	ds_read_b64 v[0:1], v0
	s_add_i32 s2, 0, 0x23488
	v_mov_b32_e32 v2, s2
	s_add_i32 s6, 0, 0x234c0
	ds_read_b64 v[8:9], v2
	s_waitcnt lgkmcnt(0)
	v_readfirstlane_b32 s2, v0
	v_mov_b32_e32 v0, s6
	s_add_i32 s6, 0, 0x234d0
	v_mov_b32_e32 v4, s6
	v_readfirstlane_b32 s3, v1
	ds_read_b128 v[0:3], v0
	ds_read_b128 v[4:7], v4
	v_readfirstlane_b32 s12, v8
	v_readfirstlane_b32 s13, v9
	s_cmpk_gt_i32 s71, 0x80f
	s_waitcnt lgkmcnt(1)
	v_readfirstlane_b32 s14, v0
	v_readfirstlane_b32 s15, v1
	v_readfirstlane_b32 s16, v2
	v_readfirstlane_b32 s17, v3
	s_waitcnt lgkmcnt(0)
	v_readfirstlane_b32 s10, v4
	v_readfirstlane_b32 s11, v5
	v_readfirstlane_b32 s8, v6
	v_readfirstlane_b32 s9, v7
	s_cbranch_scc1 .Lln2_done
	v_lshlrev_b32_e32 v0, 3, v180
	v_and_b32_e32 v56, 0x1f8, v0
	v_mov_b32_e32 v141, 0
	v_lshlrev_b32_e32 v140, 2, v56
	v_lshl_add_u64 v[32:33], s[12:13], 0, v[140:141]
	global_load_dwordx4 v[0:3], v140, s[12:13] offset:16
	global_load_dwordx4 v[4:7], v140, s[12:13]
	global_load_dwordx4 v[8:11], v140, s[12:13] offset:2064
	global_load_dwordx4 v[12:15], v140, s[12:13] offset:2048
	global_load_dwordx4 v[16:19], v140, s[14:15] offset:16
	global_load_dwordx4 v[20:23], v140, s[14:15]
	global_load_dwordx4 v[24:27], v140, s[16:17] offset:16
	global_load_dwordx4 v[28:31], v140, s[16:17]
	s_movk_i32 s12, 0x1000
	v_add_co_u32_e32 v60, vcc, s12, v32
	s_mov_b64 s[6:7], 0x1000
	s_nop 0
	v_addc_co_u32_e32 v61, vcc, 0, v33, vcc
	v_lshl_add_u64 v[58:59], v[32:33], 0, s[6:7]
	global_load_dwordx4 v[32:35], v[60:61], off
	global_load_dwordx4 v[36:39], v[58:59], off offset:16
	global_load_dwordx4 v[40:43], v140, s[10:11] offset:16
	global_load_dwordx4 v[44:47], v140, s[10:11]
	global_load_dwordx4 v[48:51], v140, s[8:9] offset:16
	global_load_dwordx4 v[52:55], v140, s[8:9]
	s_add_u32 s8, s2, 0x8340000
	s_addc_u32 s9, s3, 0
	s_add_u32 s10, s2, 0x4240000
	s_addc_u32 s11, s3, 0
	s_add_u32 s14, s2, 0x3200000
	v_lshrrev_b32_e32 v152, 6, v180
	s_addc_u32 s15, s3, 0
	s_lshl_b32 s12, s71, 3
	v_add_u32_e32 v58, s12, v152
	v_max_i32_e32 v57, 1, v58
	s_movk_i32 s13, 0xe00
	v_mov_b64_e32 v[60:61], s[8:9]
	v_add_u32_e32 v57, -1, v57
	v_mad_i64_i32 v[62:63], s[16:17], v58, s13, v[60:61]
	v_lshlrev_b32_e32 v140, 1, v56
	v_lshl_add_u64 v[62:63], v[62:63], 0, v[140:141]
	v_mad_u64_u32 v[60:61], s[16:17], v57, s13, v[60:61]
	v_ashrrev_i32_e32 v59, 31, v58
	v_lshl_add_u64 v[60:61], v[60:61], 0, v[140:141]
	global_load_dwordx4 v[104:107], v[62:63], off
	global_load_dwordx4 v[108:111], v[62:63], off offset:1024
	global_load_dwordx4 v[124:127], v[60:61], off
	global_load_dwordx4 v[92:95], v[62:63], off offset:2048
	global_load_dwordx4 v[116:119], v[60:61], off offset:1024
	global_load_dwordx4 v[120:123], v[60:61], off offset:2048
	v_lshlrev_b64 v[58:59], 10, v[58:59]
	v_lshl_add_u64 v[60:61], s[14:15], 0, v[58:59]
	v_lshl_add_u64 v[62:63], s[10:11], 0, v[58:59]
	v_lshl_add_u64 v[58:59], s[2:3], 0, v[58:59]
	v_lshl_add_u64 v[60:61], v[60:61], 0, v[140:141]
	v_lshl_add_u64 v[58:59], v[58:59], 0, v[140:141]
	v_lshl_add_u64 v[62:63], v[62:63], 0, v[140:141]
	global_load_dwordx4 v[112:115], v[60:61], off
	global_load_dwordx4 v[100:103], v[62:63], off
	global_load_dwordx4 v[96:99], v[58:59], off
	v_lshl_add_u64 v[146:147], s[2:3], 0, v[140:141]
	s_add_i32 s2, s71, s72
	v_lshl_add_u64 v[142:143], s[14:15], 0, v[140:141]
	v_lshl_add_u64 v[144:145], s[10:11], 0, v[140:141]
	v_lshl_add_u64 v[148:149], s[8:9], 0, v[140:141]
	s_lshl_b32 s14, s2, 3
	s_lshl_b32 s15, s72, 3
	s_movk_i32 s16, 0x4000
	s_movk_i32 s17, 0x3fff
	s_add_i32 s18, 0, 0x23428
	s_movk_i32 s19, 0x1c00
	v_lshlrev_b32_e32 v140, 2, v56
	v_mov_b32_e32 v153, 0x3a27c5ac
	s_mov_b32 s20, 0xf800000
	v_mov_b32_e32 v154, 0x260
	v_mov_b32_e32 v155, 0xfff
	s_mov_b32 s21, s71
	s_branch .Lln2_c
